# stack5 plus in-proj rope epilogue: each row's cos/sin loads issued one row ahead of use
# speedup vs baseline: 1.0070x; 1.0028x over previous
; __device__ __forceinline__ unsigned cvt_pk_bf16(float lo, float hi) { f32x2 v = {lo, hi}; bf16x2_t b = __builtin_convertvector(v, bf16x2_t); return __builtin_bit_cast(unsigned, b); }
;     __device__ __forceinline__ void operator()(const Acc& acc, const Unit& u, int wr, int wc, int fr, int fq) const {
;         const int row0 = u.pm * BM + wr * 64 + fr; const int sec = u.pn >> 2, tl = u.pn & 3;
;         if (sec == 2 || sec == 3) {
;             bf16_t* dst = (sec == 2) ? (HCAT + 1024) : KB; const int pitch = (sec == 2) ? 2048 : 1024; const float sc = (sec == 2) ? C2 : 1.0f;
;             const int col0 = tl * 256 + wc * 64 + 8 * fq;
; #pragma unroll
;             for (int ai = 0; ai < 2; ++ai)
; #pragma unroll
;                 for (int m = 0; m < 4; ++m) { const int row = row0 + ai * HALF + m * 16; const float* cs = rope + (size_t)(row & (SEQ - 1)) * 64 + 8 * fq;
;                     u32x4 w1, w2;
; #pragma unroll
;                     for (int n = 0; n < 2; ++n) { const f32x4 c = *(const f32x4*)(cs + 4 * n) * sc, s = *(const f32x4*)(cs + 32 + 4 * n) * sc;
;                         const f32x4 x1 = acc[ai][0][m][n], x2 = acc[ai][1][m][n]; const f32x4 o1 = x1 * c - x2 * s, o2 = x2 * c + x1 * s;
;                         w1[2 * n] = cvt_pk_bf16(o1[0], o1[1]); w1[2 * n + 1] = cvt_pk_bf16(o1[2], o1[3]); w2[2 * n] = cvt_pk_bf16(o2[0], o2[1]); w2[2 * n + 1] = cvt_pk_bf16(o2[2], o2[3]); }
;                     bf16_t* p = (sec == 2) ? dst + (size_t)row * pitch + col0
;                                            : dst + ((size_t)(((row >> 14) * 8 + tl * 2 + (wc >> 1)) * SEQ + (row & (SEQ - 1)))) * 128 + (wc & 1) * 64 + 8 * fq;
;                     *(u32x4*)p = w1; *(u32x4*)(p + 32) = w2; asm volatile("" ::: "memory"); }
.LBB0_183:
	s_and_b64 vcc, exec, s[18:19]
	s_cbranch_vccz .LBB0_302
	s_cmp_eq_u32 s93, 2
	s_cselect_b64 vcc, -1, 0
	s_lshl_b32 s12, s59, 8
	s_or_b32 s12, s12, s23
	v_lshlrev_b32_e32 v142, 3, v155
	v_add_u32_e32 v146, s12, v142
	s_lshl_b32 s12, s59, 1
	s_or_b32 s18, s12, s72
	v_readlane_b32 s12, v251, 12
	v_ashrrev_i32_e32 v147, 31, v146
	v_readlane_b32 s13, v251, 13
	v_and_b32_e32 v141, 0x3fff, v154
	v_ashrrev_i32_e32 v143, 31, v142
	v_lshl_add_u64 v[164:165], v[146:147], 1, s[12:13]
	v_readlane_b32 s12, v251, 24
	v_lshlrev_b32_e32 v192, 8, v141
	v_readlane_b32 s13, v251, 25
	v_lshl_add_u64 v[144:145], v[142:143], 1, s[8:9]
	v_lshlrev_b64 v[142:143], 2, v[142:143]
	v_lshl_add_u64 v[146:147], s[12:13], 0, v[192:193]
	v_lshl_add_u64 v[160:161], v[146:147], 0, v[142:143]
	s_mov_b64 s[98:99], 0x1000
	s_mov_b64 s[100:101], 0x5000
	global_load_dwordx4 v[232:235], v[160:161], off offset:16
	global_load_dwordx4 v[236:239], v[160:161], off
	global_load_dwordx4 v[240:243], v[160:161], off offset:144
	global_load_dwordx4 v[244:247], v[160:161], off offset:128
	v_cndmask_b32_e32 v140, 1.0, v229, vcc
	s_and_b64 s[24:25], vcc, exec
	s_cselect_b32 s19, 12, 8
	s_waitcnt vmcnt(0)
	v_lshl_add_u64 v[218:219], v[160:161], 0, s[98:99]
	v_mov_b32_e32 v146, v232
	v_mov_b32_e32 v147, v233
	v_mov_b32_e32 v148, v234
	v_mov_b32_e32 v149, v235
	v_mov_b32_e32 v156, v236
	v_mov_b32_e32 v157, v237
	v_mov_b32_e32 v158, v238
	v_mov_b32_e32 v159, v239
	v_pk_mul_f32 v[166:167], v[140:141], v[158:159] op_sel_hi:[0,1]
	v_pk_mul_f32 v[168:169], v[140:141], v[156:157] op_sel_hi:[0,1]
	v_mov_b32_e32 v156, v240
	v_mov_b32_e32 v157, v241
	v_mov_b32_e32 v158, v242
	v_mov_b32_e32 v159, v243
	v_mov_b32_e32 v160, v244
	v_mov_b32_e32 v161, v245
	v_mov_b32_e32 v162, v246
	v_mov_b32_e32 v163, v247
	global_load_dwordx4 v[232:235], v[218:219], off offset:16
	global_load_dwordx4 v[236:239], v[218:219], off
	global_load_dwordx4 v[240:243], v[218:219], off offset:144
	global_load_dwordx4 v[244:247], v[218:219], off offset:128
	v_pk_mul_f32 v[162:163], v[140:141], v[162:163] op_sel_hi:[0,1]
	v_pk_mul_f32 v[160:161], v[140:141], v[160:161] op_sel_hi:[0,1]
	v_pk_mul_f32 v[170:171], v[118:119], v[162:163]
	v_pk_mul_f32 v[172:173], v[116:117], v[160:161]
	v_pk_fma_f32 v[170:171], v[126:127], v[166:167], v[170:171] neg_lo:[0,0,1] neg_hi:[0,0,1]
	v_pk_fma_f32 v[172:173], v[124:125], v[168:169], v[172:173] neg_lo:[0,0,1] neg_hi:[0,0,1]
	v_pk_mul_f32 v[126:127], v[126:127], v[162:163]
	v_pk_mul_f32 v[124:125], v[124:125], v[160:161]
	v_pk_fma_f32 v[118:119], v[118:119], v[166:167], v[126:127]
	v_pk_fma_f32 v[124:125], v[116:117], v[168:169], v[124:125]
	v_pk_mul_f32 v[126:127], v[140:141], v[146:147] op_sel_hi:[0,1]
	v_cvt_pk_bf16_f32 v124, v124, v125
	v_cvt_pk_bf16_f32 v125, v118, v119
	v_pk_mul_f32 v[118:119], v[140:141], v[148:149] op_sel_hi:[0,1]
	v_pk_mul_f32 v[148:149], v[140:141], v[156:157] op_sel_hi:[0,1]
	v_pk_mul_f32 v[146:147], v[140:141], v[158:159] op_sel_hi:[0,1]
	v_pk_mul_f32 v[158:159], v[112:113], v[148:149]
	v_pk_mul_f32 v[156:157], v[114:115], v[146:147]
	v_pk_fma_f32 v[158:159], v[120:121], v[126:127], v[158:159] neg_lo:[0,0,1] neg_hi:[0,0,1]
	v_pk_mul_f32 v[120:121], v[120:121], v[148:149]
	v_pk_fma_f32 v[156:157], v[122:123], v[118:119], v[156:157] neg_lo:[0,0,1] neg_hi:[0,0,1]
	v_pk_fma_f32 v[112:113], v[112:113], v[126:127], v[120:121]
	v_pk_mul_f32 v[122:123], v[122:123], v[146:147]
	v_cvt_pk_bf16_f32 v126, v112, v113
	v_lshrrev_b32_e32 v112, 11, v154
	v_and_b32_e32 v112, 0x3fff8, v112
	v_or_b32_e32 v112, s18, v112
	v_pk_fma_f32 v[114:115], v[114:115], v[118:119], v[122:123]
	v_lshl_or_b32 v112, v112, 14, v141
	v_cvt_pk_bf16_f32 v127, v114, v115
	v_cndmask_b32_e32 v114, v112, v154, vcc
	v_ashrrev_i32_e32 v115, 31, v114
	v_add_u32_e32 v141, 16, v154
	v_cndmask_b32_e32 v113, v145, v165, vcc
	v_cndmask_b32_e32 v112, v144, v164, vcc
	v_lshlrev_b64 v[114:115], s19, v[114:115]
	v_and_b32_e32 v155, 0x3fff, v141
	v_cvt_pk_bf16_f32 v116, v172, v173
	v_cvt_pk_bf16_f32 v117, v170, v171
	v_cvt_pk_bf16_f32 v118, v158, v159
	v_cvt_pk_bf16_f32 v119, v156, v157
	v_lshl_add_u64 v[114:115], v[112:113], 0, v[114:115]
	v_lshlrev_b32_e32 v192, 8, v155
	global_store_dwordx4 v[114:115], v[116:119], off
	global_store_dwordx4 v[114:115], v[124:127], off offset:64
	v_lshl_add_u64 v[114:115], s[12:13], 0, v[192:193]
	v_lshl_add_u64 v[122:123], v[114:115], 0, v[142:143]
	s_waitcnt vmcnt(2)
; __device__ __forceinline__ unsigned cvt_pk_bf16(float lo, float hi) { f32x2 v = {lo, hi}; bf16x2_t b = __builtin_convertvector(v, bf16x2_t); return __builtin_bit_cast(unsigned, b); }
;     __device__ __forceinline__ void operator()(const Acc& acc, const Unit& u, int wr, int wc, int fr, int fq) const {
;     ...
;                 for (int m = 0; m < 4; ++m) { const int row = row0 + ai * HALF + m * 16; const float* cs = rope + (size_t)(row & (SEQ - 1)) * 64 + 8 * fq;
;                     u32x4 w1, w2;
; #pragma unroll
;                     for (int n = 0; n < 2; ++n) { const f32x4 c = *(const f32x4*)(cs + 4 * n) * sc, s = *(const f32x4*)(cs + 32 + 4 * n) * sc;
;                         const f32x4 x1 = acc[ai][0][m][n], x2 = acc[ai][1][m][n]; const f32x4 o1 = x1 * c - x2 * s, o2 = x2 * c + x1 * s;
;                         w1[2 * n] = cvt_pk_bf16(o1[0], o1[1]); w1[2 * n + 1] = cvt_pk_bf16(o1[2], o1[3]); w2[2 * n] = cvt_pk_bf16(o2[0], o2[1]); w2[2 * n + 1] = cvt_pk_bf16(o2[2], o2[3]); }
;                     bf16_t* p = (sec == 2) ? dst + (size_t)row * pitch + col0
;                                            : dst + ((size_t)(((row >> 14) * 8 + tl * 2 + (wc >> 1)) * SEQ + (row & (SEQ - 1)))) * 128 + (wc & 1) * 64 + 8 * fq;
;                     *(u32x4*)p = w1; *(u32x4*)(p + 32) = w2; asm volatile("" ::: "memory"); }
	v_lshl_add_u64 v[218:219], v[122:123], 0, s[98:99]
	v_mov_b32_e32 v114, v232
	v_mov_b32_e32 v115, v233
	v_mov_b32_e32 v116, v234
	v_mov_b32_e32 v117, v235
	v_mov_b32_e32 v118, v236
	v_mov_b32_e32 v119, v237
	v_mov_b32_e32 v120, v238
	v_mov_b32_e32 v121, v239
	v_pk_mul_f32 v[126:127], v[140:141], v[120:121] op_sel_hi:[0,1]
	v_pk_mul_f32 v[144:145], v[140:141], v[118:119] op_sel_hi:[0,1]
	v_mov_b32_e32 v118, v240
	v_mov_b32_e32 v119, v241
	v_mov_b32_e32 v120, v242
	v_mov_b32_e32 v121, v243
	v_mov_b32_e32 v122, v244
	v_mov_b32_e32 v123, v245
	v_mov_b32_e32 v124, v246
	v_mov_b32_e32 v125, v247
	global_load_dwordx4 v[232:235], v[218:219], off offset:16
	global_load_dwordx4 v[236:239], v[218:219], off
	global_load_dwordx4 v[240:243], v[218:219], off offset:144
	global_load_dwordx4 v[244:247], v[218:219], off offset:128
	v_pk_mul_f32 v[124:125], v[140:141], v[124:125] op_sel_hi:[0,1]
	v_pk_mul_f32 v[122:123], v[140:141], v[122:123] op_sel_hi:[0,1]
	v_pk_mul_f32 v[146:147], v[102:103], v[124:125]
	v_pk_mul_f32 v[148:149], v[100:101], v[122:123]
	v_pk_fma_f32 v[146:147], v[110:111], v[126:127], v[146:147] neg_lo:[0,0,1] neg_hi:[0,0,1]
	v_pk_fma_f32 v[148:149], v[108:109], v[144:145], v[148:149] neg_lo:[0,0,1] neg_hi:[0,0,1]
	v_pk_mul_f32 v[110:111], v[110:111], v[124:125]
	v_pk_mul_f32 v[108:109], v[108:109], v[122:123]
	v_pk_fma_f32 v[102:103], v[102:103], v[126:127], v[110:111]
	v_pk_fma_f32 v[108:109], v[100:101], v[144:145], v[108:109]
	v_pk_mul_f32 v[110:111], v[140:141], v[114:115] op_sel_hi:[0,1]
	v_cvt_pk_bf16_f32 v108, v108, v109
	v_cvt_pk_bf16_f32 v109, v102, v103
	v_pk_mul_f32 v[102:103], v[140:141], v[116:117] op_sel_hi:[0,1]
	v_pk_mul_f32 v[116:117], v[140:141], v[118:119] op_sel_hi:[0,1]
	v_pk_mul_f32 v[114:115], v[140:141], v[120:121] op_sel_hi:[0,1]
	v_pk_mul_f32 v[120:121], v[96:97], v[116:117]
	v_pk_mul_f32 v[118:119], v[98:99], v[114:115]
	v_pk_fma_f32 v[120:121], v[104:105], v[110:111], v[120:121] neg_lo:[0,0,1] neg_hi:[0,0,1]
	v_pk_mul_f32 v[104:105], v[104:105], v[116:117]
	v_pk_fma_f32 v[118:119], v[106:107], v[102:103], v[118:119] neg_lo:[0,0,1] neg_hi:[0,0,1]
	v_pk_fma_f32 v[96:97], v[96:97], v[110:111], v[104:105]
	v_pk_mul_f32 v[106:107], v[106:107], v[114:115]
	v_cvt_pk_bf16_f32 v110, v96, v97
	v_lshrrev_b32_e32 v96, 11, v141
	v_and_b32_e32 v96, 0x3fff8, v96
	v_or_b32_e32 v96, s18, v96
	v_lshl_or_b32 v96, v96, 14, v155
	v_cndmask_b32_e32 v96, v96, v141, vcc
	v_pk_fma_f32 v[98:99], v[98:99], v[102:103], v[106:107]
	v_cvt_pk_bf16_f32 v103, v118, v119
	v_ashrrev_i32_e32 v97, 31, v96
	v_add_u32_e32 v118, 32, v154
	v_lshlrev_b64 v[96:97], s19, v[96:97]
	v_and_b32_e32 v119, 0x3fff, v118
	v_cvt_pk_bf16_f32 v100, v148, v149
	v_cvt_pk_bf16_f32 v101, v146, v147
	v_cvt_pk_bf16_f32 v102, v120, v121
	v_lshl_add_u64 v[96:97], v[112:113], 0, v[96:97]
	v_lshlrev_b32_e32 v192, 8, v119
	v_cvt_pk_bf16_f32 v111, v98, v99
	global_store_dwordx4 v[96:97], v[100:103], off
	global_store_dwordx4 v[96:97], v[108:111], off offset:64
	v_lshl_add_u64 v[96:97], s[12:13], 0, v[192:193]
	v_lshl_add_u64 v[104:105], v[96:97], 0, v[142:143]
	s_waitcnt vmcnt(2)
	v_lshl_add_u64 v[218:219], v[104:105], 0, s[98:99]
	v_mov_b32_e32 v96, v232
	v_mov_b32_e32 v97, v233
	v_mov_b32_e32 v98, v234
	v_mov_b32_e32 v99, v235
	v_mov_b32_e32 v100, v236
	v_mov_b32_e32 v101, v237
	v_mov_b32_e32 v102, v238
	v_mov_b32_e32 v103, v239
	v_pk_mul_f32 v[108:109], v[140:141], v[102:103] op_sel_hi:[0,1]
	v_pk_mul_f32 v[110:111], v[140:141], v[100:101] op_sel_hi:[0,1]
	v_mov_b32_e32 v100, v240
	v_mov_b32_e32 v101, v241
	v_mov_b32_e32 v102, v242
	v_mov_b32_e32 v103, v243
	v_mov_b32_e32 v104, v244
	v_mov_b32_e32 v105, v245
	v_mov_b32_e32 v106, v246
	v_mov_b32_e32 v107, v247
	global_load_dwordx4 v[232:235], v[218:219], off offset:16
	global_load_dwordx4 v[236:239], v[218:219], off
	global_load_dwordx4 v[240:243], v[218:219], off offset:144
	global_load_dwordx4 v[244:247], v[218:219], off offset:128
	v_pk_mul_f32 v[106:107], v[140:141], v[106:107] op_sel_hi:[0,1]
	v_pk_mul_f32 v[104:105], v[140:141], v[104:105] op_sel_hi:[0,1]
	v_pk_mul_f32 v[114:115], v[86:87], v[106:107]
	v_pk_mul_f32 v[116:117], v[84:85], v[104:105]
	v_pk_fma_f32 v[114:115], v[94:95], v[108:109], v[114:115] neg_lo:[0,0,1] neg_hi:[0,0,1]
	v_pk_fma_f32 v[116:117], v[92:93], v[110:111], v[116:117] neg_lo:[0,0,1] neg_hi:[0,0,1]
	v_pk_mul_f32 v[94:95], v[94:95], v[106:107]
	v_pk_mul_f32 v[92:93], v[92:93], v[104:105]
	v_pk_fma_f32 v[86:87], v[86:87], v[108:109], v[94:95]
	v_pk_fma_f32 v[92:93], v[84:85], v[110:111], v[92:93]
	v_pk_mul_f32 v[94:95], v[140:141], v[96:97] op_sel_hi:[0,1]
	v_cvt_pk_bf16_f32 v92, v92, v93
	v_cvt_pk_bf16_f32 v93, v86, v87
	v_pk_mul_f32 v[86:87], v[140:141], v[98:99] op_sel_hi:[0,1]
	v_pk_mul_f32 v[98:99], v[140:141], v[100:101] op_sel_hi:[0,1]
	v_pk_mul_f32 v[96:97], v[140:141], v[102:103] op_sel_hi:[0,1]
	v_pk_mul_f32 v[102:103], v[80:81], v[98:99]
	v_pk_mul_f32 v[100:101], v[82:83], v[96:97]
	v_pk_fma_f32 v[102:103], v[88:89], v[94:95], v[102:103] neg_lo:[0,0,1] neg_hi:[0,0,1]
	v_pk_mul_f32 v[88:89], v[88:89], v[98:99]
	v_pk_fma_f32 v[100:101], v[90:91], v[86:87], v[100:101] neg_lo:[0,0,1] neg_hi:[0,0,1]
	v_pk_fma_f32 v[80:81], v[80:81], v[94:95], v[88:89]
	v_pk_mul_f32 v[90:91], v[90:91], v[96:97]
	v_cvt_pk_bf16_f32 v94, v80, v81
	v_lshrrev_b32_e32 v80, 11, v118
	v_and_b32_e32 v80, 0x3fff8, v80
	v_or_b32_e32 v80, s18, v80
	v_lshl_or_b32 v80, v80, 14, v119
	v_cndmask_b32_e32 v80, v80, v118, vcc
	v_pk_fma_f32 v[82:83], v[82:83], v[86:87], v[90:91]
	v_cvt_pk_bf16_f32 v87, v100, v101
	v_ashrrev_i32_e32 v81, 31, v80
	v_add_u32_e32 v100, 48, v154
	v_lshlrev_b64 v[80:81], s19, v[80:81]
	v_and_b32_e32 v101, 0x3fff, v100
	v_cvt_pk_bf16_f32 v84, v116, v117
	v_cvt_pk_bf16_f32 v85, v114, v115
	v_cvt_pk_bf16_f32 v86, v102, v103
	v_lshl_add_u64 v[80:81], v[112:113], 0, v[80:81]
	v_lshlrev_b32_e32 v192, 8, v101
	v_cvt_pk_bf16_f32 v95, v82, v83
	global_store_dwordx4 v[80:81], v[84:87], off
	global_store_dwordx4 v[80:81], v[92:95], off offset:64
	v_lshl_add_u64 v[80:81], s[12:13], 0, v[192:193]
	v_lshl_add_u64 v[88:89], v[80:81], 0, v[142:143]
	s_waitcnt vmcnt(2)
; __device__ __forceinline__ unsigned cvt_pk_bf16(float lo, float hi) { f32x2 v = {lo, hi}; bf16x2_t b = __builtin_convertvector(v, bf16x2_t); return __builtin_bit_cast(unsigned, b); }
;     __device__ __forceinline__ void operator()(const Acc& acc, const Unit& u, int wr, int wc, int fr, int fq) const {
;     ...
;                 for (int m = 0; m < 4; ++m) { const int row = row0 + ai * HALF + m * 16; const float* cs = rope + (size_t)(row & (SEQ - 1)) * 64 + 8 * fq;
;                     u32x4 w1, w2;
; #pragma unroll
;                     for (int n = 0; n < 2; ++n) { const f32x4 c = *(const f32x4*)(cs + 4 * n) * sc, s = *(const f32x4*)(cs + 32 + 4 * n) * sc;
;                         const f32x4 x1 = acc[ai][0][m][n], x2 = acc[ai][1][m][n]; const f32x4 o1 = x1 * c - x2 * s, o2 = x2 * c + x1 * s;
;                         w1[2 * n] = cvt_pk_bf16(o1[0], o1[1]); w1[2 * n + 1] = cvt_pk_bf16(o1[2], o1[3]); w2[2 * n] = cvt_pk_bf16(o2[0], o2[1]); w2[2 * n + 1] = cvt_pk_bf16(o2[2], o2[3]); }
;                     bf16_t* p = (sec == 2) ? dst + (size_t)row * pitch + col0
;                                            : dst + ((size_t)(((row >> 14) * 8 + tl * 2 + (wc >> 1)) * SEQ + (row & (SEQ - 1)))) * 128 + (wc & 1) * 64 + 8 * fq;
;                     *(u32x4*)p = w1; *(u32x4*)(p + 32) = w2; asm volatile("" ::: "memory"); }
	v_lshl_add_u64 v[218:219], v[88:89], 0, s[100:101]
	v_mov_b32_e32 v80, v232
	v_mov_b32_e32 v81, v233
	v_mov_b32_e32 v82, v234
	v_mov_b32_e32 v83, v235
	v_mov_b32_e32 v84, v236
	v_mov_b32_e32 v85, v237
	v_mov_b32_e32 v86, v238
	v_mov_b32_e32 v87, v239
	v_pk_mul_f32 v[92:93], v[140:141], v[86:87] op_sel_hi:[0,1]
	v_pk_mul_f32 v[94:95], v[140:141], v[84:85] op_sel_hi:[0,1]
	v_mov_b32_e32 v84, v240
	v_mov_b32_e32 v85, v241
	v_mov_b32_e32 v86, v242
	v_mov_b32_e32 v87, v243
	v_mov_b32_e32 v88, v244
	v_mov_b32_e32 v89, v245
	v_mov_b32_e32 v90, v246
	v_mov_b32_e32 v91, v247
	global_load_dwordx4 v[232:235], v[218:219], off offset:16
	global_load_dwordx4 v[236:239], v[218:219], off
	global_load_dwordx4 v[240:243], v[218:219], off offset:144
	global_load_dwordx4 v[244:247], v[218:219], off offset:128
	v_pk_mul_f32 v[90:91], v[140:141], v[90:91] op_sel_hi:[0,1]
	v_pk_mul_f32 v[88:89], v[140:141], v[88:89] op_sel_hi:[0,1]
	v_pk_mul_f32 v[96:97], v[70:71], v[90:91]
	v_pk_mul_f32 v[98:99], v[68:69], v[88:89]
	v_pk_fma_f32 v[96:97], v[78:79], v[92:93], v[96:97] neg_lo:[0,0,1] neg_hi:[0,0,1]
	v_pk_fma_f32 v[98:99], v[76:77], v[94:95], v[98:99] neg_lo:[0,0,1] neg_hi:[0,0,1]
	v_pk_mul_f32 v[78:79], v[78:79], v[90:91]
	v_pk_mul_f32 v[76:77], v[76:77], v[88:89]
	v_pk_fma_f32 v[70:71], v[70:71], v[92:93], v[78:79]
	v_pk_fma_f32 v[76:77], v[68:69], v[94:95], v[76:77]
	v_pk_mul_f32 v[78:79], v[140:141], v[80:81] op_sel_hi:[0,1]
	v_cvt_pk_bf16_f32 v76, v76, v77
	v_cvt_pk_bf16_f32 v77, v70, v71
	v_pk_mul_f32 v[70:71], v[140:141], v[82:83] op_sel_hi:[0,1]
	v_pk_mul_f32 v[82:83], v[140:141], v[84:85] op_sel_hi:[0,1]
	v_pk_mul_f32 v[80:81], v[140:141], v[86:87] op_sel_hi:[0,1]
	v_pk_mul_f32 v[86:87], v[64:65], v[82:83]
	v_pk_mul_f32 v[84:85], v[66:67], v[80:81]
	v_pk_fma_f32 v[86:87], v[72:73], v[78:79], v[86:87] neg_lo:[0,0,1] neg_hi:[0,0,1]
	v_pk_mul_f32 v[72:73], v[72:73], v[82:83]
	v_pk_fma_f32 v[84:85], v[74:75], v[70:71], v[84:85] neg_lo:[0,0,1] neg_hi:[0,0,1]
	v_pk_fma_f32 v[64:65], v[64:65], v[78:79], v[72:73]
	v_pk_mul_f32 v[74:75], v[74:75], v[80:81]
	v_cvt_pk_bf16_f32 v78, v64, v65
	v_lshrrev_b32_e32 v64, 11, v100
	v_and_b32_e32 v64, 0x3fff8, v64
	v_or_b32_e32 v64, s18, v64
	v_lshl_or_b32 v64, v64, 14, v101
	v_cndmask_b32_e32 v64, v64, v100, vcc
	v_pk_fma_f32 v[66:67], v[66:67], v[70:71], v[74:75]
	v_cvt_pk_bf16_f32 v71, v84, v85
	v_ashrrev_i32_e32 v65, 31, v64
	v_add_u32_e32 v84, 0x80, v154
	v_lshlrev_b64 v[64:65], s19, v[64:65]
	v_and_b32_e32 v85, 0x3fff, v84
	v_cvt_pk_bf16_f32 v68, v98, v99
	v_cvt_pk_bf16_f32 v69, v96, v97
	v_cvt_pk_bf16_f32 v70, v86, v87
	v_lshl_add_u64 v[64:65], v[112:113], 0, v[64:65]
	v_lshlrev_b32_e32 v192, 8, v85
	v_cvt_pk_bf16_f32 v79, v66, v67
	global_store_dwordx4 v[64:65], v[68:71], off
	global_store_dwordx4 v[64:65], v[76:79], off offset:64
	v_lshl_add_u64 v[64:65], s[12:13], 0, v[192:193]
	v_lshl_add_u64 v[72:73], v[64:65], 0, v[142:143]
	s_waitcnt vmcnt(2)
	v_lshl_add_u64 v[218:219], v[72:73], 0, s[98:99]
	v_mov_b32_e32 v64, v232
	v_mov_b32_e32 v65, v233
	v_mov_b32_e32 v66, v234
	v_mov_b32_e32 v67, v235
	v_mov_b32_e32 v68, v236
	v_mov_b32_e32 v69, v237
	v_mov_b32_e32 v70, v238
	v_mov_b32_e32 v71, v239
	v_pk_mul_f32 v[76:77], v[140:141], v[70:71] op_sel_hi:[0,1]
	v_pk_mul_f32 v[78:79], v[140:141], v[68:69] op_sel_hi:[0,1]
	v_mov_b32_e32 v68, v240
	v_mov_b32_e32 v69, v241
	v_mov_b32_e32 v70, v242
	v_mov_b32_e32 v71, v243
	v_mov_b32_e32 v72, v244
	v_mov_b32_e32 v73, v245
	v_mov_b32_e32 v74, v246
	v_mov_b32_e32 v75, v247
	global_load_dwordx4 v[232:235], v[218:219], off offset:16
	global_load_dwordx4 v[236:239], v[218:219], off
	global_load_dwordx4 v[240:243], v[218:219], off offset:144
	global_load_dwordx4 v[244:247], v[218:219], off offset:128
	v_pk_mul_f32 v[74:75], v[140:141], v[74:75] op_sel_hi:[0,1]
	v_pk_mul_f32 v[72:73], v[140:141], v[72:73] op_sel_hi:[0,1]
	v_pk_mul_f32 v[80:81], v[54:55], v[74:75]
	v_pk_mul_f32 v[82:83], v[52:53], v[72:73]
	v_pk_fma_f32 v[80:81], v[62:63], v[76:77], v[80:81] neg_lo:[0,0,1] neg_hi:[0,0,1]
	v_pk_fma_f32 v[82:83], v[60:61], v[78:79], v[82:83] neg_lo:[0,0,1] neg_hi:[0,0,1]
	v_pk_mul_f32 v[62:63], v[62:63], v[74:75]
	v_pk_mul_f32 v[60:61], v[60:61], v[72:73]
	v_pk_fma_f32 v[54:55], v[54:55], v[76:77], v[62:63]
	v_pk_fma_f32 v[60:61], v[52:53], v[78:79], v[60:61]
	v_pk_mul_f32 v[62:63], v[140:141], v[64:65] op_sel_hi:[0,1]
	v_cvt_pk_bf16_f32 v60, v60, v61
	v_cvt_pk_bf16_f32 v61, v54, v55
	v_pk_mul_f32 v[54:55], v[140:141], v[66:67] op_sel_hi:[0,1]
	v_pk_mul_f32 v[66:67], v[140:141], v[68:69] op_sel_hi:[0,1]
	v_pk_mul_f32 v[64:65], v[140:141], v[70:71] op_sel_hi:[0,1]
	v_pk_mul_f32 v[70:71], v[48:49], v[66:67]
	v_pk_mul_f32 v[68:69], v[50:51], v[64:65]
	v_pk_fma_f32 v[70:71], v[56:57], v[62:63], v[70:71] neg_lo:[0,0,1] neg_hi:[0,0,1]
	v_pk_mul_f32 v[56:57], v[56:57], v[66:67]
	v_pk_fma_f32 v[68:69], v[58:59], v[54:55], v[68:69] neg_lo:[0,0,1] neg_hi:[0,0,1]
	v_pk_fma_f32 v[48:49], v[48:49], v[62:63], v[56:57]
	v_pk_mul_f32 v[58:59], v[58:59], v[64:65]
	v_cvt_pk_bf16_f32 v62, v48, v49
	v_lshrrev_b32_e32 v48, 11, v84
	v_and_b32_e32 v48, 0x3fff8, v48
	v_or_b32_e32 v48, s18, v48
	v_lshl_or_b32 v48, v48, 14, v85
	v_cndmask_b32_e32 v48, v48, v84, vcc
	v_pk_fma_f32 v[50:51], v[50:51], v[54:55], v[58:59]
	v_cvt_pk_bf16_f32 v55, v68, v69
	v_ashrrev_i32_e32 v49, 31, v48
	v_add_u32_e32 v68, 0x90, v154
	v_lshlrev_b64 v[48:49], s19, v[48:49]
	v_and_b32_e32 v69, 0x3fff, v68
	v_cvt_pk_bf16_f32 v52, v82, v83
	v_cvt_pk_bf16_f32 v53, v80, v81
	v_cvt_pk_bf16_f32 v54, v70, v71
	v_lshl_add_u64 v[48:49], v[112:113], 0, v[48:49]
	v_lshlrev_b32_e32 v192, 8, v69
	v_cvt_pk_bf16_f32 v63, v50, v51
	global_store_dwordx4 v[48:49], v[52:55], off
	global_store_dwordx4 v[48:49], v[60:63], off offset:64
	v_lshl_add_u64 v[48:49], s[12:13], 0, v[192:193]
	v_lshl_add_u64 v[56:57], v[48:49], 0, v[142:143]
	s_waitcnt vmcnt(2)
; __device__ __forceinline__ unsigned cvt_pk_bf16(float lo, float hi) { f32x2 v = {lo, hi}; bf16x2_t b = __builtin_convertvector(v, bf16x2_t); return __builtin_bit_cast(unsigned, b); }
;     __device__ __forceinline__ void operator()(const Acc& acc, const Unit& u, int wr, int wc, int fr, int fq) const {
;     ...
;                 for (int m = 0; m < 4; ++m) { const int row = row0 + ai * HALF + m * 16; const float* cs = rope + (size_t)(row & (SEQ - 1)) * 64 + 8 * fq;
;                     u32x4 w1, w2;
; #pragma unroll
;                     for (int n = 0; n < 2; ++n) { const f32x4 c = *(const f32x4*)(cs + 4 * n) * sc, s = *(const f32x4*)(cs + 32 + 4 * n) * sc;
;                         const f32x4 x1 = acc[ai][0][m][n], x2 = acc[ai][1][m][n]; const f32x4 o1 = x1 * c - x2 * s, o2 = x2 * c + x1 * s;
;                         w1[2 * n] = cvt_pk_bf16(o1[0], o1[1]); w1[2 * n + 1] = cvt_pk_bf16(o1[2], o1[3]); w2[2 * n] = cvt_pk_bf16(o2[0], o2[1]); w2[2 * n + 1] = cvt_pk_bf16(o2[2], o2[3]); }
;                     bf16_t* p = (sec == 2) ? dst + (size_t)row * pitch + col0
;                                            : dst + ((size_t)(((row >> 14) * 8 + tl * 2 + (wc >> 1)) * SEQ + (row & (SEQ - 1)))) * 128 + (wc & 1) * 64 + 8 * fq;
;                     *(u32x4*)p = w1; *(u32x4*)(p + 32) = w2; asm volatile("" ::: "memory"); }
	v_lshl_add_u64 v[218:219], v[56:57], 0, s[98:99]
	v_mov_b32_e32 v48, v232
	v_mov_b32_e32 v49, v233
	v_mov_b32_e32 v50, v234
	v_mov_b32_e32 v51, v235
	v_mov_b32_e32 v52, v236
	v_mov_b32_e32 v53, v237
	v_mov_b32_e32 v54, v238
	v_mov_b32_e32 v55, v239
	v_pk_mul_f32 v[60:61], v[140:141], v[54:55] op_sel_hi:[0,1]
	v_pk_mul_f32 v[62:63], v[140:141], v[52:53] op_sel_hi:[0,1]
	v_mov_b32_e32 v52, v240
	v_mov_b32_e32 v53, v241
	v_mov_b32_e32 v54, v242
	v_mov_b32_e32 v55, v243
	v_mov_b32_e32 v56, v244
	v_mov_b32_e32 v57, v245
	v_mov_b32_e32 v58, v246
	v_mov_b32_e32 v59, v247
	global_load_dwordx4 v[232:235], v[218:219], off offset:16
	global_load_dwordx4 v[236:239], v[218:219], off
	global_load_dwordx4 v[240:243], v[218:219], off offset:144
	global_load_dwordx4 v[244:247], v[218:219], off offset:128
	v_pk_mul_f32 v[58:59], v[140:141], v[58:59] op_sel_hi:[0,1]
	v_pk_mul_f32 v[56:57], v[140:141], v[56:57] op_sel_hi:[0,1]
	v_pk_mul_f32 v[64:65], v[38:39], v[58:59]
	v_pk_mul_f32 v[66:67], v[36:37], v[56:57]
	v_pk_fma_f32 v[64:65], v[46:47], v[60:61], v[64:65] neg_lo:[0,0,1] neg_hi:[0,0,1]
	v_pk_fma_f32 v[66:67], v[44:45], v[62:63], v[66:67] neg_lo:[0,0,1] neg_hi:[0,0,1]
	v_pk_mul_f32 v[46:47], v[46:47], v[58:59]
	v_pk_mul_f32 v[44:45], v[44:45], v[56:57]
	v_pk_fma_f32 v[38:39], v[38:39], v[60:61], v[46:47]
	v_pk_fma_f32 v[44:45], v[36:37], v[62:63], v[44:45]
	v_pk_mul_f32 v[46:47], v[140:141], v[48:49] op_sel_hi:[0,1]
	v_cvt_pk_bf16_f32 v44, v44, v45
	v_cvt_pk_bf16_f32 v45, v38, v39
	v_pk_mul_f32 v[38:39], v[140:141], v[50:51] op_sel_hi:[0,1]
	v_pk_mul_f32 v[50:51], v[140:141], v[52:53] op_sel_hi:[0,1]
	v_pk_mul_f32 v[48:49], v[140:141], v[54:55] op_sel_hi:[0,1]
	v_pk_mul_f32 v[54:55], v[32:33], v[50:51]
	v_pk_mul_f32 v[52:53], v[34:35], v[48:49]
	v_pk_fma_f32 v[54:55], v[40:41], v[46:47], v[54:55] neg_lo:[0,0,1] neg_hi:[0,0,1]
	v_pk_mul_f32 v[40:41], v[40:41], v[50:51]
	v_pk_fma_f32 v[52:53], v[42:43], v[38:39], v[52:53] neg_lo:[0,0,1] neg_hi:[0,0,1]
	v_pk_fma_f32 v[32:33], v[32:33], v[46:47], v[40:41]
	v_pk_mul_f32 v[42:43], v[42:43], v[48:49]
	v_cvt_pk_bf16_f32 v46, v32, v33
	v_lshrrev_b32_e32 v32, 11, v68
	v_and_b32_e32 v32, 0x3fff8, v32
	v_or_b32_e32 v32, s18, v32
	v_lshl_or_b32 v32, v32, 14, v69
	v_cndmask_b32_e32 v32, v32, v68, vcc
	v_pk_fma_f32 v[34:35], v[34:35], v[38:39], v[42:43]
	v_cvt_pk_bf16_f32 v39, v52, v53
	v_ashrrev_i32_e32 v33, 31, v32
	v_add_u32_e32 v52, 0xa0, v154
	v_lshlrev_b64 v[32:33], s19, v[32:33]
	v_and_b32_e32 v53, 0x3fff, v52
	v_cvt_pk_bf16_f32 v36, v66, v67
	v_cvt_pk_bf16_f32 v37, v64, v65
	v_cvt_pk_bf16_f32 v38, v54, v55
	v_lshl_add_u64 v[32:33], v[112:113], 0, v[32:33]
	v_lshlrev_b32_e32 v192, 8, v53
	v_cvt_pk_bf16_f32 v47, v34, v35
	global_store_dwordx4 v[32:33], v[36:39], off
	global_store_dwordx4 v[32:33], v[44:47], off offset:64
	v_lshl_add_u64 v[32:33], s[12:13], 0, v[192:193]
	v_lshl_add_u64 v[40:41], v[32:33], 0, v[142:143]
	s_waitcnt vmcnt(2)
; __device__ __forceinline__ unsigned cvt_pk_bf16(float lo, float hi) { f32x2 v = {lo, hi}; bf16x2_t b = __builtin_convertvector(v, bf16x2_t); return __builtin_bit_cast(unsigned, b); }
;     __device__ __forceinline__ void operator()(const Acc& acc, const Unit& u, int wr, int wc, int fr, int fq) const {
;     ...
;                 for (int m = 0; m < 4; ++m) { const int row = row0 + ai * HALF + m * 16; const float* cs = rope + (size_t)(row & (SEQ - 1)) * 64 + 8 * fq;
;                     u32x4 w1, w2;
; #pragma unroll
;                     for (int n = 0; n < 2; ++n) { const f32x4 c = *(const f32x4*)(cs + 4 * n) * sc, s = *(const f32x4*)(cs + 32 + 4 * n) * sc;
;                         const f32x4 x1 = acc[ai][0][m][n], x2 = acc[ai][1][m][n]; const f32x4 o1 = x1 * c - x2 * s, o2 = x2 * c + x1 * s;
;                         w1[2 * n] = cvt_pk_bf16(o1[0], o1[1]); w1[2 * n + 1] = cvt_pk_bf16(o1[2], o1[3]); w2[2 * n] = cvt_pk_bf16(o2[0], o2[1]); w2[2 * n + 1] = cvt_pk_bf16(o2[2], o2[3]); }
;                     bf16_t* p = (sec == 2) ? dst + (size_t)row * pitch + col0
;                                            : dst + ((size_t)(((row >> 14) * 8 + tl * 2 + (wc >> 1)) * SEQ + (row & (SEQ - 1)))) * 128 + (wc & 1) * 64 + 8 * fq;
;                     *(u32x4*)p = w1; *(u32x4*)(p + 32) = w2; asm volatile("" ::: "memory"); }
;             return;
;         }
	v_lshl_add_u64 v[218:219], v[40:41], 0, s[98:99]
	v_mov_b32_e32 v32, v232
	v_mov_b32_e32 v33, v233
	v_mov_b32_e32 v34, v234
	v_mov_b32_e32 v35, v235
	v_mov_b32_e32 v36, v236
	v_mov_b32_e32 v37, v237
	v_mov_b32_e32 v38, v238
	v_mov_b32_e32 v39, v239
	v_pk_mul_f32 v[44:45], v[140:141], v[38:39] op_sel_hi:[0,1]
	v_pk_mul_f32 v[46:47], v[140:141], v[36:37] op_sel_hi:[0,1]
	v_mov_b32_e32 v36, v240
	v_mov_b32_e32 v37, v241
	v_mov_b32_e32 v38, v242
	v_mov_b32_e32 v39, v243
	v_mov_b32_e32 v40, v244
	v_mov_b32_e32 v41, v245
	v_mov_b32_e32 v42, v246
	v_mov_b32_e32 v43, v247
	global_load_dwordx4 v[232:235], v[218:219], off offset:16
	global_load_dwordx4 v[236:239], v[218:219], off
	global_load_dwordx4 v[240:243], v[218:219], off offset:144
	global_load_dwordx4 v[244:247], v[218:219], off offset:128
	v_pk_mul_f32 v[42:43], v[140:141], v[42:43] op_sel_hi:[0,1]
	v_pk_mul_f32 v[40:41], v[140:141], v[40:41] op_sel_hi:[0,1]
	v_pk_mul_f32 v[48:49], v[22:23], v[42:43]
	v_pk_mul_f32 v[50:51], v[20:21], v[40:41]
	v_pk_fma_f32 v[48:49], v[30:31], v[44:45], v[48:49] neg_lo:[0,0,1] neg_hi:[0,0,1]
	v_pk_fma_f32 v[50:51], v[28:29], v[46:47], v[50:51] neg_lo:[0,0,1] neg_hi:[0,0,1]
	v_pk_mul_f32 v[30:31], v[30:31], v[42:43]
	v_pk_mul_f32 v[28:29], v[28:29], v[40:41]
	v_pk_fma_f32 v[22:23], v[22:23], v[44:45], v[30:31]
	v_pk_fma_f32 v[28:29], v[20:21], v[46:47], v[28:29]
	v_pk_mul_f32 v[30:31], v[140:141], v[32:33] op_sel_hi:[0,1]
	v_cvt_pk_bf16_f32 v28, v28, v29
	v_cvt_pk_bf16_f32 v29, v22, v23
	v_pk_mul_f32 v[22:23], v[140:141], v[34:35] op_sel_hi:[0,1]
	v_pk_mul_f32 v[34:35], v[140:141], v[36:37] op_sel_hi:[0,1]
	v_pk_mul_f32 v[32:33], v[140:141], v[38:39] op_sel_hi:[0,1]
	v_pk_mul_f32 v[38:39], v[16:17], v[34:35]
	v_pk_mul_f32 v[36:37], v[18:19], v[32:33]
	v_pk_fma_f32 v[38:39], v[24:25], v[30:31], v[38:39] neg_lo:[0,0,1] neg_hi:[0,0,1]
	v_pk_mul_f32 v[24:25], v[24:25], v[34:35]
	v_pk_fma_f32 v[36:37], v[26:27], v[22:23], v[36:37] neg_lo:[0,0,1] neg_hi:[0,0,1]
	v_pk_fma_f32 v[16:17], v[16:17], v[30:31], v[24:25]
	v_pk_mul_f32 v[26:27], v[26:27], v[32:33]
	v_cvt_pk_bf16_f32 v30, v16, v17
	v_lshrrev_b32_e32 v16, 11, v52
	v_and_b32_e32 v16, 0x3fff8, v16
	v_or_b32_e32 v16, s18, v16
	v_lshl_or_b32 v16, v16, 14, v53
	v_cndmask_b32_e32 v16, v16, v52, vcc
	v_pk_fma_f32 v[18:19], v[18:19], v[22:23], v[26:27]
	v_cvt_pk_bf16_f32 v23, v36, v37
	v_ashrrev_i32_e32 v17, 31, v16
	v_add_u32_e32 v36, 0xb0, v154
	v_lshlrev_b64 v[16:17], s19, v[16:17]
	v_and_b32_e32 v37, 0x3fff, v36
	v_cvt_pk_bf16_f32 v20, v50, v51
	v_cvt_pk_bf16_f32 v21, v48, v49
	v_cvt_pk_bf16_f32 v22, v38, v39
	v_lshl_add_u64 v[16:17], v[112:113], 0, v[16:17]
	v_lshlrev_b32_e32 v192, 8, v37
	v_cvt_pk_bf16_f32 v31, v18, v19
	global_store_dwordx4 v[16:17], v[20:23], off
	global_store_dwordx4 v[16:17], v[28:31], off offset:64
	v_lshl_add_u64 v[16:17], s[12:13], 0, v[192:193]
	v_lshl_add_u64 v[24:25], v[16:17], 0, v[142:143]
	s_waitcnt vmcnt(2)
	v_mov_b32_e32 v16, v232
	v_mov_b32_e32 v17, v233
	v_mov_b32_e32 v18, v234
	v_mov_b32_e32 v19, v235
	v_mov_b32_e32 v20, v236
	v_mov_b32_e32 v21, v237
	v_mov_b32_e32 v22, v238
	v_mov_b32_e32 v23, v239
	v_pk_mul_f32 v[28:29], v[140:141], v[22:23] op_sel_hi:[0,1]
	v_pk_mul_f32 v[30:31], v[140:141], v[20:21] op_sel_hi:[0,1]
	v_mov_b32_e32 v20, v240
	v_mov_b32_e32 v21, v241
	v_mov_b32_e32 v22, v242
	v_mov_b32_e32 v23, v243
	v_mov_b32_e32 v24, v244
	v_mov_b32_e32 v25, v245
	v_mov_b32_e32 v26, v246
	v_mov_b32_e32 v27, v247
	v_pk_mul_f32 v[26:27], v[140:141], v[26:27] op_sel_hi:[0,1]
	v_pk_mul_f32 v[24:25], v[140:141], v[24:25] op_sel_hi:[0,1]
	v_pk_mul_f32 v[32:33], v[6:7], v[26:27]
	v_pk_mul_f32 v[34:35], v[4:5], v[24:25]
	v_pk_fma_f32 v[32:33], v[14:15], v[28:29], v[32:33] neg_lo:[0,0,1] neg_hi:[0,0,1]
	v_pk_fma_f32 v[34:35], v[12:13], v[30:31], v[34:35] neg_lo:[0,0,1] neg_hi:[0,0,1]
	v_pk_mul_f32 v[14:15], v[14:15], v[26:27]
	v_pk_mul_f32 v[12:13], v[12:13], v[24:25]
	v_pk_fma_f32 v[6:7], v[6:7], v[28:29], v[14:15]
	v_pk_fma_f32 v[12:13], v[4:5], v[30:31], v[12:13]
	v_pk_mul_f32 v[14:15], v[140:141], v[16:17] op_sel_hi:[0,1]
	v_cvt_pk_bf16_f32 v12, v12, v13
	v_cvt_pk_bf16_f32 v13, v6, v7
	v_pk_mul_f32 v[6:7], v[140:141], v[18:19] op_sel_hi:[0,1]
	v_pk_mul_f32 v[18:19], v[140:141], v[20:21] op_sel_hi:[0,1]
	v_pk_mul_f32 v[16:17], v[140:141], v[22:23] op_sel_hi:[0,1]
	v_pk_mul_f32 v[22:23], v[0:1], v[18:19]
	v_pk_mul_f32 v[20:21], v[2:3], v[16:17]
	v_pk_fma_f32 v[22:23], v[8:9], v[14:15], v[22:23] neg_lo:[0,0,1] neg_hi:[0,0,1]
	v_pk_mul_f32 v[8:9], v[8:9], v[18:19]
	v_pk_fma_f32 v[20:21], v[10:11], v[6:7], v[20:21] neg_lo:[0,0,1] neg_hi:[0,0,1]
	v_pk_fma_f32 v[0:1], v[0:1], v[14:15], v[8:9]
	v_pk_mul_f32 v[10:11], v[10:11], v[16:17]
	v_cvt_pk_bf16_f32 v14, v0, v1
	v_lshrrev_b32_e32 v0, 11, v36
	v_and_b32_e32 v0, 0x3fff8, v0
	v_or_b32_e32 v0, s18, v0
	v_lshl_or_b32 v0, v0, 14, v37
	v_cndmask_b32_e32 v0, v0, v36, vcc
	v_ashrrev_i32_e32 v1, 31, v0
	v_lshlrev_b64 v[0:1], s19, v[0:1]
	v_cvt_pk_bf16_f32 v4, v34, v35
	v_cvt_pk_bf16_f32 v5, v32, v33
	v_pk_fma_f32 v[2:3], v[2:3], v[6:7], v[10:11]
	v_cvt_pk_bf16_f32 v6, v22, v23
	v_cvt_pk_bf16_f32 v7, v20, v21
	v_lshl_add_u64 v[0:1], v[112:113], 0, v[0:1]
	v_cvt_pk_bf16_f32 v15, v2, v3
	global_store_dwordx4 v[0:1], v[4:7], off
	global_store_dwordx4 v[0:1], v[12:15], off offset:64
	s_andn2_b64 vcc, exec, s[42:43]
	s_mov_b64 s[18:19], -1
	s_cbranch_vccnz .LBB0_163
	s_branch .LBB0_303
